# v14 + kv-up-projection epilogue: rope/KR/cos/sin loads of each row group issued together with its ssq load (3 of 4 store-draining waits per group removed)
# speedup vs baseline: 1.0163x; 1.0038x over previous
.LBB0_640:
	s_lshl_b32 s2, s2, 8
	v_add_u32_e32 v194, s2, v145
	v_ashrrev_i32_e32 v195, 31, v194
	v_lshl_add_u64 v[80:81], v[194:195], 2, s[22:23]
	global_load_dword v80, v[80:81], off
	s_waitcnt vmcnt(0)
	v_fmamk_f32 v80, v80, 0x3b000000, v197
	v_cmp_gt_f32_e32 vcc, s36, v80
	v_mul_f32_e32 v81, 0x4f800000, v80
	s_nop 0
	v_cndmask_b32_e32 v80, v80, v81, vcc
	v_sqrt_f32_e32 v81, v80
	s_nop 0
	v_add_u32_e32 v82, -1, v81
	v_fma_f32 v83, -v82, v81, v80
	v_cmp_ge_f32_e64 s[12:13], 0, v83
	v_add_u32_e32 v83, 1, v81
	s_nop 0
	v_cndmask_b32_e64 v82, v81, v82, s[12:13]
	v_fma_f32 v81, -v83, v81, v80
	v_cmp_lt_f32_e64 s[12:13], 0, v81
	s_nop 1
	v_cndmask_b32_e64 v81, v82, v83, s[12:13]
	v_mul_f32_e32 v82, 0x37800000, v81
	v_cndmask_b32_e32 v81, v81, v82, vcc
	v_cmp_class_f32_e32 vcc, v80, v198
	s_nop 1
	v_cndmask_b32_e32 v80, v81, v80, vcc
	v_div_scale_f32 v81, s[12:13], v80, v80, 1.0
	v_rcp_f32_e32 v82, v81
	s_nop 0
	v_fma_f32 v83, -v81, v82, 1.0
	v_fmac_f32_e32 v82, v83, v82
	v_div_scale_f32 v83, vcc, 1.0, v80, 1.0
	v_mul_f32_e32 v84, v83, v82
	v_fma_f32 v85, -v81, v84, v83
	v_fmac_f32_e32 v84, v85, v82
	v_fma_f32 v81, -v81, v84, v83
	v_div_fmas_f32 v81, v81, v82, v84
	v_div_fixup_f32 v196, v81, v80, 1.0
	v_mul_f32_e32 v80, v133, v133
	v_mul_f32_e32 v81, v135, v135
	v_fmac_f32_e32 v80, v132, v132
	v_fmac_f32_e32 v81, v134, v134
	v_add_f32_e32 v80, v80, v81
	v_mul_f32_e32 v81, v129, v129
	v_fmac_f32_e32 v81, v128, v128
	v_add_f32_e32 v80, v80, v81
	v_mul_f32_e32 v81, v131, v131
	v_fmac_f32_e32 v81, v130, v130
	v_add_f32_e32 v80, v81, v80
	v_mov_b32_e32 v81, v80
	s_nop 1
	v_permlane16_swap_b32_e32 v80, v81
	v_add_f32_e32 v80, v80, v81
	v_mov_b32_e32 v81, v80
	s_nop 1
	v_permlane32_swap_b32_e32 v80, v81
	s_and_saveexec_b64 s[12:13], s[8:9]
	v_add_f32_e32 v80, v80, v81
	v_mul_f32_e32 v80, v196, v80
	v_mul_f32_e32 v80, v196, v80
	v_add_u32_e32 v81, s93, v254
	ds_write_b32 v81, v80
	s_or_b64 exec, exec, s[12:13]
	v_add_u32_e32 v190, s2, v253
	v_ashrrev_i32_e32 v191, 31, v190
	v_lshl_add_u64 v[80:81], v[190:191], 2, s[22:23]
	global_load_dword v80, v[80:81], off
	s_waitcnt vmcnt(0)
	v_fmamk_f32 v80, v80, 0x3b000000, v197
	v_cmp_gt_f32_e32 vcc, s36, v80
	v_mul_f32_e32 v81, 0x4f800000, v80
	s_nop 0
	v_cndmask_b32_e32 v80, v80, v81, vcc
	v_sqrt_f32_e32 v81, v80
	s_nop 0
	v_add_u32_e32 v82, -1, v81
	v_fma_f32 v83, -v82, v81, v80
	v_cmp_ge_f32_e64 s[12:13], 0, v83
	v_add_u32_e32 v83, 1, v81
	s_nop 0
	v_cndmask_b32_e64 v82, v81, v82, s[12:13]
	v_fma_f32 v81, -v83, v81, v80
	v_cmp_lt_f32_e64 s[12:13], 0, v81
	s_nop 1
	v_cndmask_b32_e64 v81, v82, v83, s[12:13]
	v_mul_f32_e32 v82, 0x37800000, v81
	v_cndmask_b32_e32 v81, v81, v82, vcc
	v_cmp_class_f32_e32 vcc, v80, v198
	s_nop 1
	v_cndmask_b32_e32 v80, v81, v80, vcc
	v_div_scale_f32 v81, s[12:13], v80, v80, 1.0
	v_rcp_f32_e32 v82, v81
	s_nop 0
	v_fma_f32 v83, -v81, v82, 1.0
	v_fmac_f32_e32 v82, v83, v82
	v_div_scale_f32 v83, vcc, 1.0, v80, 1.0
	v_mul_f32_e32 v84, v83, v82
	v_fma_f32 v85, -v81, v84, v83
	v_fmac_f32_e32 v84, v85, v82
	v_fma_f32 v81, -v81, v84, v83
	v_div_fmas_f32 v81, v81, v82, v84
	v_div_fixup_f32 v192, v81, v80, 1.0
	v_mul_f32_e32 v80, v117, v117
	v_mul_f32_e32 v81, v119, v119
	v_fmac_f32_e32 v80, v116, v116
	v_fmac_f32_e32 v81, v118, v118
	v_add_f32_e32 v80, v80, v81
	v_mul_f32_e32 v81, v113, v113
	v_fmac_f32_e32 v81, v112, v112
	v_add_f32_e32 v80, v80, v81
	v_mul_f32_e32 v81, v115, v115
	v_fmac_f32_e32 v81, v114, v114
	v_add_f32_e32 v80, v81, v80
	v_mov_b32_e32 v81, v80
	s_nop 1
	v_permlane16_swap_b32_e32 v80, v81
	v_add_f32_e32 v80, v80, v81
	v_mov_b32_e32 v81, v80
	s_nop 1
	v_permlane32_swap_b32_e32 v80, v81
	s_and_saveexec_b64 s[12:13], s[8:9]
	v_add_f32_e32 v80, v80, v81
	v_mul_f32_e32 v80, v192, v80
	v_mul_f32_e32 v80, v192, v80
	v_add_u32_e32 v81, s93, v181
	ds_write_b32 v81, v80
	s_or_b64 exec, exec, s[12:13]
	v_add_u32_e32 v186, s2, v252
	v_ashrrev_i32_e32 v187, 31, v186
	v_lshl_add_u64 v[80:81], v[186:187], 2, s[22:23]
	global_load_dword v80, v[80:81], off
	s_waitcnt vmcnt(0)
	v_fmamk_f32 v80, v80, 0x3b000000, v197
	v_cmp_gt_f32_e32 vcc, s36, v80
	v_mul_f32_e32 v81, 0x4f800000, v80
	s_nop 0
	v_cndmask_b32_e32 v80, v80, v81, vcc
	v_sqrt_f32_e32 v81, v80
	s_nop 0
	v_add_u32_e32 v82, -1, v81
	v_fma_f32 v83, -v82, v81, v80
	v_cmp_ge_f32_e64 s[12:13], 0, v83
	v_add_u32_e32 v83, 1, v81
	s_nop 0
	v_cndmask_b32_e64 v82, v81, v82, s[12:13]
	v_fma_f32 v81, -v83, v81, v80
	v_cmp_lt_f32_e64 s[12:13], 0, v81
	s_nop 1
	v_cndmask_b32_e64 v81, v82, v83, s[12:13]
	v_mul_f32_e32 v82, 0x37800000, v81
	v_cndmask_b32_e32 v81, v81, v82, vcc
	v_cmp_class_f32_e32 vcc, v80, v198
	s_nop 1
	v_cndmask_b32_e32 v80, v81, v80, vcc
	v_div_scale_f32 v81, s[12:13], v80, v80, 1.0
	v_rcp_f32_e32 v82, v81
	s_nop 0
	v_fma_f32 v83, -v81, v82, 1.0
	v_fmac_f32_e32 v82, v83, v82
	v_div_scale_f32 v83, vcc, 1.0, v80, 1.0
	v_mul_f32_e32 v84, v83, v82
	v_fma_f32 v85, -v81, v84, v83
	v_fmac_f32_e32 v84, v85, v82
	v_fma_f32 v81, -v81, v84, v83
	v_div_fmas_f32 v81, v81, v82, v84
	v_div_fixup_f32 v188, v81, v80, 1.0
	v_mul_f32_e32 v80, v101, v101
	v_mul_f32_e32 v81, v103, v103
	v_fmac_f32_e32 v80, v100, v100
	v_fmac_f32_e32 v81, v102, v102
	v_add_f32_e32 v80, v80, v81
	v_mul_f32_e32 v81, v97, v97
	v_fmac_f32_e32 v81, v96, v96
	v_add_f32_e32 v80, v80, v81
	v_mul_f32_e32 v81, v99, v99
	v_fmac_f32_e32 v81, v98, v98
	v_add_f32_e32 v80, v81, v80
	v_mov_b32_e32 v81, v80
	s_nop 1
	v_permlane16_swap_b32_e32 v80, v81
	v_add_f32_e32 v80, v80, v81
	v_mov_b32_e32 v81, v80
	s_nop 1
	v_permlane32_swap_b32_e32 v80, v81
	s_and_saveexec_b64 s[12:13], s[8:9]
	s_movk_i32 s74, 0xfdf
	s_movk_i32 s75, 0xfef
	s_movk_i32 s77, 0xfff
	v_add_f32_e32 v80, v80, v81
	v_mul_f32_e32 v80, v188, v80
	v_mul_f32_e32 v80, v188, v80
	v_add_u32_e32 v81, s93, v189
	ds_write_b32 v81, v80
	s_or_b64 exec, exec, s[12:13]
	v_add_u32_e32 v182, s2, v204
	v_ashrrev_i32_e32 v183, 31, v182
	v_lshl_add_u64 v[80:81], v[182:183], 2, s[22:23]
	global_load_dword v80, v[80:81], off
	s_waitcnt vmcnt(0)
	v_fmamk_f32 v80, v80, 0x3b000000, v197
	v_cmp_gt_f32_e32 vcc, s36, v80
	v_mul_f32_e32 v81, 0x4f800000, v80
	s_nop 0
	v_cndmask_b32_e32 v80, v80, v81, vcc
	v_sqrt_f32_e32 v81, v80
	s_nop 0
	v_add_u32_e32 v82, -1, v81
	v_fma_f32 v83, -v82, v81, v80
	v_cmp_ge_f32_e64 s[12:13], 0, v83
	v_add_u32_e32 v83, 1, v81
	s_nop 0
	v_cndmask_b32_e64 v82, v81, v82, s[12:13]
	v_fma_f32 v81, -v83, v81, v80
	v_cmp_lt_f32_e64 s[12:13], 0, v81
	s_nop 1
	v_cndmask_b32_e64 v81, v82, v83, s[12:13]
	v_mul_f32_e32 v82, 0x37800000, v81
	v_cndmask_b32_e32 v81, v81, v82, vcc
	v_cmp_class_f32_e32 vcc, v80, v198
	s_nop 1
	v_cndmask_b32_e32 v80, v81, v80, vcc
	v_div_scale_f32 v81, s[12:13], v80, v80, 1.0
	v_rcp_f32_e32 v82, v81
	s_nop 0
	v_fma_f32 v83, -v81, v82, 1.0
	v_fmac_f32_e32 v82, v83, v82
	v_div_scale_f32 v83, vcc, 1.0, v80, 1.0
	v_mul_f32_e32 v84, v83, v82
	v_fma_f32 v85, -v81, v84, v83
	v_fmac_f32_e32 v84, v85, v82
	v_fma_f32 v81, -v81, v84, v83
	v_div_fmas_f32 v81, v81, v82, v84
	v_div_fixup_f32 v184, v81, v80, 1.0
	v_mul_f32_e32 v80, v77, v77
	v_mul_f32_e32 v81, v79, v79
	v_fmac_f32_e32 v80, v76, v76
	v_fmac_f32_e32 v81, v78, v78
	v_add_f32_e32 v80, v80, v81
	v_mul_f32_e32 v81, v73, v73
	v_fmac_f32_e32 v81, v72, v72
	v_add_f32_e32 v80, v80, v81
	v_mul_f32_e32 v81, v75, v75
	v_fmac_f32_e32 v81, v74, v74
	v_add_f32_e32 v80, v81, v80
	v_mov_b32_e32 v81, v80
	s_nop 1
	v_permlane16_swap_b32_e32 v80, v81
	v_add_f32_e32 v80, v80, v81
	v_mov_b32_e32 v81, v80
	s_nop 1
	v_permlane32_swap_b32_e32 v80, v81
	s_and_saveexec_b64 s[12:13], s[8:9]
	v_add_f32_e32 v80, v80, v81
	v_mul_f32_e32 v80, v184, v80
	v_mul_f32_e32 v80, v184, v80
	v_add_u32_e32 v81, s93, v205
	ds_write_b32 v81, v80
	s_or_b64 exec, exec, s[12:13]
	v_add_u32_e32 v174, s2, v206
	v_ashrrev_i32_e32 v175, 31, v174
	v_lshl_add_u64 v[80:81], v[174:175], 2, s[22:23]
	global_load_dword v80, v[80:81], off
	s_waitcnt vmcnt(0)
	v_fmamk_f32 v80, v80, 0x3b000000, v197
	v_cmp_gt_f32_e32 vcc, s36, v80
	v_mul_f32_e32 v81, 0x4f800000, v80
	s_nop 0
	v_cndmask_b32_e32 v80, v80, v81, vcc
	v_sqrt_f32_e32 v81, v80
	s_nop 0
	v_add_u32_e32 v82, -1, v81
	v_fma_f32 v83, -v82, v81, v80
	v_cmp_ge_f32_e64 s[12:13], 0, v83
	v_add_u32_e32 v83, 1, v81
	s_nop 0
	v_cndmask_b32_e64 v82, v81, v82, s[12:13]
	v_fma_f32 v81, -v83, v81, v80
	v_cmp_lt_f32_e64 s[12:13], 0, v81
	s_nop 1
	v_cndmask_b32_e64 v81, v82, v83, s[12:13]
	v_mul_f32_e32 v82, 0x37800000, v81
	v_cndmask_b32_e32 v81, v81, v82, vcc
	v_cmp_class_f32_e32 vcc, v80, v198
	s_nop 1
	v_cndmask_b32_e32 v80, v81, v80, vcc
	v_div_scale_f32 v81, s[12:13], v80, v80, 1.0
	v_rcp_f32_e32 v82, v81
	s_nop 0
	v_fma_f32 v83, -v81, v82, 1.0
	v_fmac_f32_e32 v82, v83, v82
	v_div_scale_f32 v83, vcc, 1.0, v80, 1.0
	v_mul_f32_e32 v84, v83, v82
	v_fma_f32 v85, -v81, v84, v83
	v_fmac_f32_e32 v84, v85, v82
	v_fma_f32 v81, -v81, v84, v83
	v_div_fmas_f32 v81, v81, v82, v84
	v_div_fixup_f32 v180, v81, v80, 1.0
	v_mul_f32_e32 v80, v61, v61
	v_mul_f32_e32 v81, v63, v63
	v_fmac_f32_e32 v80, v60, v60
	v_fmac_f32_e32 v81, v62, v62
	v_add_f32_e32 v80, v80, v81
	v_mul_f32_e32 v81, v57, v57
	v_fmac_f32_e32 v81, v56, v56
	v_add_f32_e32 v80, v80, v81
	v_mul_f32_e32 v81, v59, v59
	v_fmac_f32_e32 v81, v58, v58
	v_add_f32_e32 v80, v81, v80
	v_mov_b32_e32 v81, v80
	s_nop 1
	v_permlane16_swap_b32_e32 v80, v81
	v_add_f32_e32 v80, v80, v81
	v_mov_b32_e32 v81, v80
	s_nop 1
	v_permlane32_swap_b32_e32 v80, v81
	s_and_saveexec_b64 s[12:13], s[8:9]
	v_add_f32_e32 v80, v80, v81
	v_mul_f32_e32 v80, v180, v80
	v_mul_f32_e32 v80, v180, v80
	v_add_u32_e32 v81, s93, v207
	ds_write_b32 v81, v80
	s_or_b64 exec, exec, s[12:13]
	v_add_u32_e32 v170, s2, v208
	v_ashrrev_i32_e32 v171, 31, v170
	v_lshl_add_u64 v[80:81], v[170:171], 2, s[22:23]
	global_load_dword v80, v[80:81], off
	s_waitcnt vmcnt(0)
	v_fmamk_f32 v80, v80, 0x3b000000, v197
	v_cmp_gt_f32_e32 vcc, s36, v80
	v_mul_f32_e32 v81, 0x4f800000, v80
	s_nop 0
	v_cndmask_b32_e32 v80, v80, v81, vcc
	v_sqrt_f32_e32 v81, v80
	s_nop 0
	v_add_u32_e32 v82, -1, v81
	v_fma_f32 v83, -v82, v81, v80
	v_cmp_ge_f32_e64 s[12:13], 0, v83
	v_add_u32_e32 v83, 1, v81
	s_nop 0
	v_cndmask_b32_e64 v82, v81, v82, s[12:13]
	v_fma_f32 v81, -v83, v81, v80
	v_cmp_lt_f32_e64 s[12:13], 0, v81
	s_nop 1
	v_cndmask_b32_e64 v81, v82, v83, s[12:13]
	v_mul_f32_e32 v82, 0x37800000, v81
	v_cndmask_b32_e32 v81, v81, v82, vcc
	v_cmp_class_f32_e32 vcc, v80, v198
	s_nop 1
	v_cndmask_b32_e32 v80, v81, v80, vcc
	v_div_scale_f32 v81, s[12:13], v80, v80, 1.0
	v_rcp_f32_e32 v82, v81
	s_nop 0
	v_fma_f32 v83, -v81, v82, 1.0
	v_fmac_f32_e32 v82, v83, v82
	v_div_scale_f32 v83, vcc, 1.0, v80, 1.0
	v_mul_f32_e32 v84, v83, v82
	v_fma_f32 v85, -v81, v84, v83
	v_fmac_f32_e32 v84, v85, v82
	v_fma_f32 v81, -v81, v84, v83
	v_div_fmas_f32 v81, v81, v82, v84
	v_div_fixup_f32 v172, v81, v80, 1.0
	v_mul_f32_e32 v80, v45, v45
	v_mul_f32_e32 v81, v47, v47
	v_fmac_f32_e32 v80, v44, v44
	v_fmac_f32_e32 v81, v46, v46
	v_add_f32_e32 v80, v80, v81
	v_mul_f32_e32 v81, v41, v41
	v_fmac_f32_e32 v81, v40, v40
	v_add_f32_e32 v80, v80, v81
	v_mul_f32_e32 v81, v43, v43
	v_fmac_f32_e32 v81, v42, v42
	v_add_f32_e32 v80, v81, v80
	v_mov_b32_e32 v81, v80
	s_nop 1
	v_permlane16_swap_b32_e32 v80, v81
	v_add_f32_e32 v80, v80, v81
	v_mov_b32_e32 v81, v80
	s_nop 1
	v_permlane32_swap_b32_e32 v80, v81
	s_and_saveexec_b64 s[12:13], s[8:9]
	v_add_f32_e32 v80, v80, v81
	v_mul_f32_e32 v80, v172, v80
	v_mul_f32_e32 v80, v172, v80
	v_add_u32_e32 v81, s93, v209
	ds_write_b32 v81, v80
	s_or_b64 exec, exec, s[12:13]
	v_add_u32_e32 v166, s2, v210
	v_ashrrev_i32_e32 v167, 31, v166
	v_lshl_add_u64 v[80:81], v[166:167], 2, s[22:23]
	global_load_dword v80, v[80:81], off
	s_waitcnt vmcnt(0)
	v_fmamk_f32 v80, v80, 0x3b000000, v197
	v_cmp_gt_f32_e32 vcc, s36, v80
	v_mul_f32_e32 v81, 0x4f800000, v80
	s_nop 0
	v_cndmask_b32_e32 v80, v80, v81, vcc
	v_sqrt_f32_e32 v81, v80
	s_nop 0
	v_add_u32_e32 v82, -1, v81
	v_fma_f32 v83, -v82, v81, v80
	v_cmp_ge_f32_e64 s[12:13], 0, v83
	v_add_u32_e32 v83, 1, v81
	s_nop 0
	v_cndmask_b32_e64 v82, v81, v82, s[12:13]
	v_fma_f32 v81, -v83, v81, v80
	v_cmp_lt_f32_e64 s[12:13], 0, v81
	s_nop 1
	v_cndmask_b32_e64 v81, v82, v83, s[12:13]
	v_mul_f32_e32 v82, 0x37800000, v81
	v_cndmask_b32_e32 v81, v81, v82, vcc
	v_cmp_class_f32_e32 vcc, v80, v198
	s_nop 1
	v_cndmask_b32_e32 v80, v81, v80, vcc
	v_div_scale_f32 v81, s[12:13], v80, v80, 1.0
	v_rcp_f32_e32 v82, v81
	s_nop 0
	v_fma_f32 v83, -v81, v82, 1.0
	v_fmac_f32_e32 v82, v83, v82
	v_div_scale_f32 v83, vcc, 1.0, v80, 1.0
	v_mul_f32_e32 v84, v83, v82
	v_fma_f32 v85, -v81, v84, v83
	v_fmac_f32_e32 v84, v85, v82
	v_fma_f32 v81, -v81, v84, v83
	v_div_fmas_f32 v81, v81, v82, v84
	v_div_fixup_f32 v168, v81, v80, 1.0
	v_mul_f32_e32 v80, v29, v29
	v_mul_f32_e32 v81, v31, v31
	v_fmac_f32_e32 v80, v28, v28
	v_fmac_f32_e32 v81, v30, v30
	v_add_f32_e32 v80, v80, v81
	v_mul_f32_e32 v81, v25, v25
	v_fmac_f32_e32 v81, v24, v24
	v_add_f32_e32 v80, v80, v81
	v_mul_f32_e32 v81, v27, v27
	v_fmac_f32_e32 v81, v26, v26
	v_add_f32_e32 v80, v81, v80
	v_mov_b32_e32 v81, v80
	s_nop 1
	v_permlane16_swap_b32_e32 v80, v81
	v_add_f32_e32 v80, v80, v81
	v_mov_b32_e32 v81, v80
	s_nop 1
	v_permlane32_swap_b32_e32 v80, v81
	s_and_saveexec_b64 s[12:13], s[8:9]
	v_add_f32_e32 v80, v80, v81
	v_mul_f32_e32 v80, v168, v80
	v_mul_f32_e32 v80, v168, v80
	v_add_u32_e32 v81, s93, v211
	ds_write_b32 v81, v80
	s_or_b64 exec, exec, s[12:13]
	v_add_u32_e32 v158, s2, v212
	v_ashrrev_i32_e32 v159, 31, v158
	v_lshl_add_u64 v[80:81], v[158:159], 2, s[22:23]
	global_load_dword v80, v[80:81], off
	s_waitcnt vmcnt(0)
	v_fmamk_f32 v80, v80, 0x3b000000, v197
	v_cmp_gt_f32_e32 vcc, s36, v80
	v_mul_f32_e32 v81, 0x4f800000, v80
	s_nop 0
	v_cndmask_b32_e32 v80, v80, v81, vcc
	v_sqrt_f32_e32 v81, v80
	s_nop 0
	v_add_u32_e32 v82, -1, v81
	v_fma_f32 v83, -v82, v81, v80
	v_cmp_ge_f32_e64 s[12:13], 0, v83
	v_add_u32_e32 v83, 1, v81
	s_nop 0
	v_cndmask_b32_e64 v82, v81, v82, s[12:13]
	v_fma_f32 v81, -v83, v81, v80
	v_cmp_lt_f32_e64 s[12:13], 0, v81
	s_nop 1
	v_cndmask_b32_e64 v81, v82, v83, s[12:13]
	v_mul_f32_e32 v82, 0x37800000, v81
	v_cndmask_b32_e32 v81, v81, v82, vcc
	v_cmp_class_f32_e32 vcc, v80, v198
	s_nop 1
	v_cndmask_b32_e32 v80, v81, v80, vcc
	v_div_scale_f32 v81, s[2:3], v80, v80, 1.0
	v_rcp_f32_e32 v82, v81
	s_nop 0
	v_fma_f32 v83, -v81, v82, 1.0
	v_fmac_f32_e32 v82, v83, v82
	v_div_scale_f32 v83, vcc, 1.0, v80, 1.0
	v_mul_f32_e32 v84, v83, v82
	v_fma_f32 v85, -v81, v84, v83
	v_fmac_f32_e32 v84, v85, v82
	v_fma_f32 v81, -v81, v84, v83
	v_div_fmas_f32 v81, v81, v82, v84
	v_div_fixup_f32 v164, v81, v80, 1.0
	v_mul_f32_e32 v80, v13, v13
	v_mul_f32_e32 v81, v15, v15
	v_fmac_f32_e32 v80, v12, v12
	v_fmac_f32_e32 v81, v14, v14
	v_add_f32_e32 v80, v80, v81
	v_mul_f32_e32 v81, v9, v9
	v_fmac_f32_e32 v81, v8, v8
	v_add_f32_e32 v80, v80, v81
	v_mul_f32_e32 v81, v11, v11
	v_fmac_f32_e32 v81, v10, v10
	v_add_f32_e32 v80, v81, v80
	v_mov_b32_e32 v81, v80
	s_nop 1
	v_permlane16_swap_b32_e32 v80, v81
	v_add_f32_e32 v80, v80, v81
	v_mov_b32_e32 v81, v80
	s_nop 1
	v_permlane32_swap_b32_e32 v80, v81
	s_and_saveexec_b64 s[12:13], s[8:9]
	v_add_f32_e32 v80, v80, v81
	v_mul_f32_e32 v80, v164, v80
	v_mul_f32_e32 v80, v164, v80
	v_add_u32_e32 v81, s93, v213
	ds_write_b32 v81, v80
	s_or_b64 exec, exec, s[12:13]
	s_add_i32 s31, 0, 0x20000
	s_waitcnt lgkmcnt(0)
	s_barrier
	v_add_u32_e32 v169, s31, v254
	global_load_dwordx4 v[80:83], v[150:151], off offset:16
	global_load_dwordx4 v[84:87], v[150:151], off
	global_load_dwordx2 v[162:163], v[152:153], off offset:512
	global_load_dwordx2 v[160:161], v[152:153], off offset:640
	ds_read_b128 v[200:203], v169
	s_movk_i32 s4, 0xfcf
	v_pk_mul_f32 v[124:125], v[124:125], v[196:197] op_sel_hi:[1,0]
	v_pk_mul_f32 v[126:127], v[126:127], v[196:197] op_sel_hi:[1,0]
	v_pk_mul_f32 v[108:109], v[108:109], v[192:193] op_sel_hi:[1,0]
	s_waitcnt lgkmcnt(0)
	v_mov_b32_e32 v216, v201
	v_mov_b32_e32 v217, v202
	v_mov_b32_e32 v201, v203
	v_pk_add_f32 v[200:201], v[216:217], v[200:201]
	v_pk_mul_f32 v[110:111], v[110:111], v[192:193] op_sel_hi:[1,0]
	v_add_f32_e32 v169, v200, v201
	v_lshl_add_u64 v[200:201], v[194:195], 2, s[24:25]
	global_load_dword v173, v[200:201], off
	v_lshlrev_b64 v[248:249], 8, v[194:195]
	v_lshl_add_u64 v[248:249], v[148:149], 0, v[248:249]
	global_load_dwordx2 v[240:241], v[248:249], off
	global_load_dwordx2 v[242:243], v[248:249], off offset:128
	v_lshlrev_b64 v[248:249], 7, v[194:195]
	v_lshlrev_b32_e32 v250, 2, v144
	v_or_b32_e32 v248, v248, v250
	v_lshl_add_u64 v[250:251], s[16:17], 0, v[248:249]
	v_lshl_add_u64 v[248:249], s[26:27], 0, v[248:249]
	global_load_dwordx2 v[244:245], v[250:251], off
	global_load_dwordx2 v[246:247], v[248:249], off
	v_pk_mul_f32 v[92:93], v[92:93], v[188:189] op_sel_hi:[1,0]
	v_pk_mul_f32 v[94:95], v[94:95], v[188:189] op_sel_hi:[1,0]
	v_pk_mul_f32 v[52:53], v[52:53], v[180:181] op_sel_hi:[1,0]
	v_pk_mul_f32 v[54:55], v[54:55], v[180:181] op_sel_hi:[1,0]
	v_pk_mul_f32 v[4:5], v[4:5], v[164:165] op_sel_hi:[1,0]
	v_pk_mul_f32 v[6:7], v[6:7], v[164:165] op_sel_hi:[1,0]
	s_waitcnt vmcnt(0)
	v_add_f32_e32 v169, v173, v169
	v_fmamk_f32 v169, v169, 0x3baaaaab, v197
	v_cmp_gt_f32_e32 vcc, s36, v169
	v_mul_f32_e32 v173, 0x4f800000, v169
	s_nop 0
	v_cndmask_b32_e32 v169, v169, v173, vcc
	v_sqrt_f32_e32 v173, v169
	s_nop 0
	v_add_u32_e32 v185, -1, v173
	v_fma_f32 v200, -v185, v173, v169
	v_cmp_ge_f32_e64 s[12:13], 0, v200
	v_add_u32_e32 v200, 1, v173
	s_nop 0
	v_cndmask_b32_e64 v185, v173, v185, s[12:13]
	v_fma_f32 v173, -v200, v173, v169
	v_cmp_lt_f32_e64 s[12:13], 0, v173
	s_nop 1
	v_cndmask_b32_e64 v173, v185, v200, s[12:13]
	v_mul_f32_e32 v185, 0x37800000, v173
	v_cndmask_b32_e32 v173, v173, v185, vcc
	v_cmp_class_f32_e32 vcc, v169, v198
	s_nop 1
	v_cndmask_b32_e32 v169, v173, v169, vcc
	v_div_scale_f32 v173, s[2:3], v169, v169, 1.0
	v_rcp_f32_e32 v185, v173
	s_nop 0
	v_fma_f32 v200, -v173, v185, 1.0
	v_fmac_f32_e32 v185, v200, v185
	v_div_scale_f32 v200, vcc, 1.0, v169, 1.0
	v_mul_f32_e32 v201, v200, v185
	v_fma_f32 v202, -v173, v201, v200
	v_fmac_f32_e32 v201, v202, v185
	v_fma_f32 v173, -v173, v201, v200
	v_div_fmas_f32 v173, v173, v185, v201
	v_div_fixup_f32 v215, v173, v169, 1.0
	v_ashrrev_i32_e32 v169, 8, v194
	v_and_b32_e32 v169, -16, v169
	v_mul_f32_e32 v200, v196, v215
	v_add_u32_e32 v202, s95, v169
	v_ashrrev_i32_e32 v203, 31, v202
	v_pk_mul_f32 v[132:133], v[132:133], v[200:201] op_sel_hi:[1,0]
	v_pk_mul_f32 v[134:135], v[134:135], v[200:201] op_sel_hi:[1,0]
	v_pk_mul_f32 v[128:129], v[128:129], v[200:201] op_sel_hi:[1,0]
	v_lshlrev_b64 v[202:203], 12, v[202:203]
	v_pk_mul_f32 v[134:135], v[86:87], v[134:135]
	v_pk_mul_f32 v[132:133], v[84:85], v[132:133]
	v_pk_mul_f32 v[130:131], v[130:131], v[200:201] op_sel_hi:[1,0]
	v_pk_mul_f32 v[128:129], v[80:81], v[128:129]
	v_and_or_b32 v202, v194, s4, v202
	v_pk_mul_f32 v[130:131], v[82:83], v[130:131]
	v_cvt_pk_bf16_f32 v132, v132, v133
	v_cvt_pk_bf16_f32 v133, v134, v135
	v_cvt_pk_bf16_f32 v134, v128, v129
	v_mov_b64_e32 v[128:129], s[20:21]
	v_cvt_pk_bf16_f32 v135, v130, v131
	v_mad_u64_u32 v[130:131], s[2:3], v202, s35, v[128:129]
	v_mad_i32_i24 v131, v203, s35, v131
	v_lshl_add_u64 v[200:201], v[130:131], 0, v[176:177]
	global_store_dwordx4 v[200:201], v[132:135], off
	v_pk_mul_f32 v[68:69], v[68:69], v[184:185] op_sel_hi:[1,0]
	v_pk_mul_f32 v[70:71], v[70:71], v[184:185] op_sel_hi:[1,0]
	v_pk_mul_f32 v[132:133], v[122:123], v[196:197] op_sel_hi:[1,0]
	v_pk_mul_f32 v[122:123], v[120:121], v[196:197] op_sel_hi:[1,0]
	v_cvt_pk_bf16_f32 v120, v124, v125
	v_lshlrev_b64 v[124:125], 8, v[202:203]
	v_cvt_pk_bf16_f32 v121, v126, v127
	v_lshl_add_u64 v[124:125], v[146:147], 0, v[124:125]
	v_cvt_pk_bf16_f32 v122, v122, v123
	v_cvt_pk_bf16_f32 v123, v132, v133
	global_store_dwordx4 v[124:125], v[120:123], off
	v_pk_mul_f32 v[36:37], v[36:37], v[172:173] op_sel_hi:[1,0]
	v_pk_mul_f32 v[38:39], v[38:39], v[172:173] op_sel_hi:[1,0]
	v_lshlrev_b64 v[120:121], 8, v[194:195]
	v_lshl_add_u64 v[120:121], v[148:149], 0, v[120:121]
	v_mov_b64_e32 v[122:123], v[240:241]
	v_pk_mul_f32 v[20:21], v[20:21], v[168:169] op_sel_hi:[1,0]
	v_mov_b64_e32 v[120:121], v[242:243]
	v_pk_mul_f32 v[22:23], v[22:23], v[168:169] op_sel_hi:[1,0]
	s_nop 0
	v_mul_f32_e32 v122, v215, v122
	v_mul_f32_e32 v132, v162, v122
	s_nop 0
	v_mul_f32_e32 v120, v215, v120
	v_mul_f32_e32 v122, v215, v123
	v_mul_f32_e32 v133, v160, v120
	v_mul_f32_e32 v120, v215, v121
	v_mul_f32_e32 v123, v163, v122
	v_mul_f32_e32 v134, v161, v120
	v_lshlrev_b64 v[120:121], 7, v[194:195]
	v_lshlrev_b32_e32 v122, 2, v144
	v_or_b32_e32 v120, v120, v122
	v_lshl_add_u64 v[124:125], s[16:17], 0, v[120:121]
	v_lshl_add_u64 v[120:121], s[26:27], 0, v[120:121]
	v_mov_b64_e32 v[124:125], v[244:245]
	s_nop 0
	v_mov_b64_e32 v[126:127], v[246:247]
	s_nop 0
	v_mul_f32_e32 v120, v133, v126
	v_mul_f32_e32 v121, v134, v127
	v_fma_f32 v120, v132, v124, -v120
	v_fma_f32 v121, v123, v125, -v121
	v_cvt_pk_bf16_f32 v135, v120, v121
	v_lshlrev_b32_e32 v120, 1, v144
	v_mov_b32_e32 v121, v177
	v_mul_f32_e32 v123, v123, v127
	v_lshl_add_u64 v[130:131], v[130:131], 0, v[120:121]
	v_mul_f32_e32 v126, v132, v126
	v_fmac_f32_e32 v123, v134, v125
	global_store_dword v[130:131], v135, off offset:256
	v_fmac_f32_e32 v126, v133, v124
	v_cvt_pk_bf16_f32 v123, v126, v123
	global_store_dword v[130:131], v123, off offset:320
	v_add_u32_e32 v123, s31, v181
	ds_read_b128 v[124:127], v123
	s_waitcnt lgkmcnt(0)
	v_mov_b32_e32 v130, v125
	v_mov_b32_e32 v131, v126
	v_mov_b32_e32 v125, v127
	v_pk_add_f32 v[124:125], v[130:131], v[124:125]
	s_nop 0
	v_add_f32_e32 v123, v124, v125
	v_lshl_add_u64 v[124:125], v[190:191], 2, s[24:25]
	global_load_dword v124, v[124:125], off
	v_lshlrev_b64 v[248:249], 8, v[190:191]
	v_lshl_add_u64 v[248:249], v[148:149], 0, v[248:249]
	global_load_dwordx2 v[240:241], v[248:249], off
	global_load_dwordx2 v[242:243], v[248:249], off offset:128
	v_lshlrev_b64 v[248:249], 7, v[190:191]
	v_lshlrev_b32_e32 v250, 2, v144
	v_or_b32_e32 v248, v248, v250
	v_lshl_add_u64 v[250:251], s[16:17], 0, v[248:249]
	v_lshl_add_u64 v[248:249], s[26:27], 0, v[248:249]
	global_load_dwordx2 v[244:245], v[250:251], off
	global_load_dwordx2 v[246:247], v[248:249], off
	s_waitcnt vmcnt(0)
	v_add_f32_e32 v123, v124, v123
	v_fmamk_f32 v123, v123, 0x3baaaaab, v197
	v_cmp_gt_f32_e32 vcc, s36, v123
	v_mul_f32_e32 v124, 0x4f800000, v123
	s_nop 0
	v_cndmask_b32_e32 v123, v123, v124, vcc
	v_sqrt_f32_e32 v124, v123
	s_nop 0
	v_add_u32_e32 v125, -1, v124
	v_fma_f32 v126, -v125, v124, v123
	v_cmp_ge_f32_e64 s[12:13], 0, v126
	v_add_u32_e32 v126, 1, v124
	s_nop 0
	v_cndmask_b32_e64 v125, v124, v125, s[12:13]
	v_fma_f32 v124, -v126, v124, v123
	v_cmp_lt_f32_e64 s[12:13], 0, v124
	s_nop 1
	v_cndmask_b32_e64 v124, v125, v126, s[12:13]
	v_mul_f32_e32 v125, 0x37800000, v124
	v_cndmask_b32_e32 v124, v124, v125, vcc
	v_cmp_class_f32_e32 vcc, v123, v198
	s_nop 1
	v_cndmask_b32_e32 v123, v124, v123, vcc
	v_div_scale_f32 v124, s[2:3], v123, v123, 1.0
	v_rcp_f32_e32 v125, v124
	s_nop 0
	v_fma_f32 v126, -v124, v125, 1.0
	v_fmac_f32_e32 v125, v126, v125
	v_div_scale_f32 v126, vcc, 1.0, v123, 1.0
	v_mul_f32_e32 v127, v126, v125
	v_fma_f32 v130, -v124, v127, v126
	v_fmac_f32_e32 v127, v130, v125
	v_fma_f32 v124, -v124, v127, v126
	v_div_fmas_f32 v124, v124, v125, v127
	v_ashrrev_i32_e32 v125, 8, v190
	v_and_b32_e32 v125, -16, v125
	v_div_fixup_f32 v123, v124, v123, 1.0
	v_add_u32_e32 v126, s95, v125
	v_mul_f32_e32 v124, v192, v123
	v_ashrrev_i32_e32 v127, 31, v126
	v_lshlrev_b64 v[126:127], 12, v[126:127]
	v_pk_mul_f32 v[116:117], v[116:117], v[124:125] op_sel_hi:[1,0]
	v_pk_mul_f32 v[112:113], v[112:113], v[124:125] op_sel_hi:[1,0]
	v_and_or_b32 v126, v190, s74, v126
	v_pk_mul_f32 v[118:119], v[118:119], v[124:125] op_sel_hi:[1,0]
	v_pk_mul_f32 v[116:117], v[84:85], v[116:117]
	v_pk_mul_f32 v[114:115], v[114:115], v[124:125] op_sel_hi:[1,0]
	v_pk_mul_f32 v[112:113], v[80:81], v[112:113]
	v_pk_mul_f32 v[118:119], v[86:87], v[118:119]
	v_pk_mul_f32 v[124:125], v[82:83], v[114:115]
	v_cvt_pk_bf16_f32 v114, v116, v117
	v_cvt_pk_bf16_f32 v115, v118, v119
	v_cvt_pk_bf16_f32 v116, v112, v113
	v_mad_u64_u32 v[112:113], s[2:3], v126, s35, v[128:129]
	v_mad_i32_i24 v113, v127, s35, v113
	v_lshl_add_u64 v[118:119], v[112:113], 0, v[176:177]
	v_cvt_pk_bf16_f32 v117, v124, v125
	global_store_dwordx4 v[118:119], v[114:117], off
	s_nop 1
	v_pk_mul_f32 v[114:115], v[106:107], v[192:193] op_sel_hi:[1,0]
	v_pk_mul_f32 v[106:107], v[104:105], v[192:193] op_sel_hi:[1,0]
	v_cvt_pk_bf16_f32 v104, v108, v109
	v_lshlrev_b64 v[108:109], 8, v[126:127]
	v_cvt_pk_bf16_f32 v105, v110, v111
	v_lshl_add_u64 v[108:109], v[146:147], 0, v[108:109]
	v_cvt_pk_bf16_f32 v106, v106, v107
	v_cvt_pk_bf16_f32 v107, v114, v115
	global_store_dwordx4 v[108:109], v[104:107], off
	s_nop 1
	v_lshlrev_b64 v[104:105], 8, v[190:191]
	v_lshl_add_u64 v[104:105], v[148:149], 0, v[104:105]
	v_mov_b64_e32 v[106:107], v[240:241]
	s_nop 0
	v_mul_f32_e32 v106, v123, v106
	v_mov_b64_e32 v[104:105], v[242:243]
	v_mul_f32_e32 v110, v162, v106
	v_mul_f32_e32 v106, v123, v107
	v_mul_f32_e32 v111, v163, v106
	s_nop 0
	v_mul_f32_e32 v104, v123, v104
	v_mul_f32_e32 v114, v160, v104
	v_mul_f32_e32 v104, v123, v105
	v_mul_f32_e32 v115, v161, v104
	v_lshlrev_b64 v[104:105], 7, v[190:191]
	v_or_b32_e32 v104, v104, v122
	v_lshl_add_u64 v[106:107], s[16:17], 0, v[104:105]
	v_lshl_add_u64 v[104:105], s[26:27], 0, v[104:105]
	v_mov_b64_e32 v[106:107], v[244:245]
	s_nop 0
	v_mov_b64_e32 v[104:105], v[246:247]
	s_nop 0
	v_mul_f32_e32 v108, v114, v104
	v_mul_f32_e32 v109, v115, v105
	v_fma_f32 v108, v110, v106, -v108
	v_fma_f32 v109, v111, v107, -v109
	v_mul_f32_e32 v104, v110, v104
	v_cvt_pk_bf16_f32 v116, v108, v109
	v_lshl_add_u64 v[108:109], v[112:113], 0, v[120:121]
	v_fmac_f32_e32 v104, v114, v106
	v_mul_f32_e32 v105, v111, v105
	global_store_dword v[108:109], v116, off offset:256
	v_fmac_f32_e32 v105, v115, v107
	v_cvt_pk_bf16_f32 v104, v104, v105
	global_store_dword v[108:109], v104, off offset:320
	v_add_u32_e32 v104, s31, v189
	ds_read_b128 v[104:107], v104
	s_waitcnt lgkmcnt(0)
	v_mov_b32_e32 v108, v105
	v_mov_b32_e32 v109, v106
	v_mov_b32_e32 v105, v107
	v_pk_add_f32 v[104:105], v[108:109], v[104:105]
	s_nop 0
	v_add_f32_e32 v106, v104, v105
	v_lshl_add_u64 v[104:105], v[186:187], 2, s[24:25]
	global_load_dword v104, v[104:105], off
	v_lshlrev_b64 v[248:249], 8, v[186:187]
	v_lshl_add_u64 v[248:249], v[148:149], 0, v[248:249]
	global_load_dwordx2 v[240:241], v[248:249], off
	global_load_dwordx2 v[242:243], v[248:249], off offset:128
	v_lshlrev_b64 v[248:249], 7, v[186:187]
	v_lshlrev_b32_e32 v250, 2, v144
	v_or_b32_e32 v248, v248, v250
	v_lshl_add_u64 v[250:251], s[16:17], 0, v[248:249]
	v_lshl_add_u64 v[248:249], s[26:27], 0, v[248:249]
	global_load_dwordx2 v[244:245], v[250:251], off
	global_load_dwordx2 v[246:247], v[248:249], off
	s_waitcnt vmcnt(0)
	v_add_f32_e32 v104, v104, v106
	v_fmamk_f32 v104, v104, 0x3baaaaab, v197
	v_cmp_gt_f32_e32 vcc, s36, v104
	v_mul_f32_e32 v105, 0x4f800000, v104
	s_nop 0
	v_cndmask_b32_e32 v104, v104, v105, vcc
	v_sqrt_f32_e32 v105, v104
	s_nop 0
	v_add_u32_e32 v106, -1, v105
	v_fma_f32 v107, -v106, v105, v104
	v_cmp_ge_f32_e64 s[12:13], 0, v107
	v_add_u32_e32 v107, 1, v105
	s_nop 0
	v_cndmask_b32_e64 v106, v105, v106, s[12:13]
	v_fma_f32 v105, -v107, v105, v104
	v_cmp_lt_f32_e64 s[12:13], 0, v105
	s_nop 1
	v_cndmask_b32_e64 v105, v106, v107, s[12:13]
	v_mul_f32_e32 v106, 0x37800000, v105
	v_cndmask_b32_e32 v105, v105, v106, vcc
	v_cmp_class_f32_e32 vcc, v104, v198
	s_nop 1
	v_cndmask_b32_e32 v104, v105, v104, vcc
	v_div_scale_f32 v105, s[2:3], v104, v104, 1.0
	v_rcp_f32_e32 v106, v105
	s_nop 0
	v_fma_f32 v107, -v105, v106, 1.0
	v_fmac_f32_e32 v106, v107, v106
	v_div_scale_f32 v107, vcc, 1.0, v104, 1.0
	v_mul_f32_e32 v108, v107, v106
	v_fma_f32 v109, -v105, v108, v107
	v_fmac_f32_e32 v108, v109, v106
	v_fma_f32 v105, -v105, v108, v107
	v_div_fmas_f32 v105, v105, v106, v108
	v_div_fixup_f32 v104, v105, v104, 1.0
	v_ashrrev_i32_e32 v105, 8, v186
	v_and_b32_e32 v105, -16, v105
	v_add_u32_e32 v108, s95, v105
	v_mul_f32_e32 v106, v188, v104
	v_ashrrev_i32_e32 v109, 31, v108
	v_lshlrev_b64 v[108:109], 12, v[108:109]
	v_pk_mul_f32 v[100:101], v[100:101], v[106:107] op_sel_hi:[1,0]
	v_pk_mul_f32 v[96:97], v[96:97], v[106:107] op_sel_hi:[1,0]
	v_and_or_b32 v108, v186, s75, v108
	v_pk_mul_f32 v[102:103], v[102:103], v[106:107] op_sel_hi:[1,0]
	v_pk_mul_f32 v[100:101], v[84:85], v[100:101]
	v_pk_mul_f32 v[98:99], v[98:99], v[106:107] op_sel_hi:[1,0]
	v_pk_mul_f32 v[96:97], v[80:81], v[96:97]
	v_pk_mul_f32 v[102:103], v[86:87], v[102:103]
	v_pk_mul_f32 v[106:107], v[82:83], v[98:99]
	v_cvt_pk_bf16_f32 v98, v100, v101
	v_cvt_pk_bf16_f32 v99, v102, v103
	v_cvt_pk_bf16_f32 v100, v96, v97
	v_mad_u64_u32 v[96:97], s[2:3], v108, s35, v[128:129]
	v_mad_i32_i24 v97, v109, s35, v97
	v_lshl_add_u64 v[102:103], v[96:97], 0, v[176:177]
	v_cvt_pk_bf16_f32 v101, v106, v107
	global_store_dwordx4 v[102:103], v[98:101], off
	s_nop 1
	v_pk_mul_f32 v[98:99], v[90:91], v[188:189] op_sel_hi:[1,0]
	v_pk_mul_f32 v[90:91], v[88:89], v[188:189] op_sel_hi:[1,0]
	v_cvt_pk_bf16_f32 v88, v92, v93
	v_lshlrev_b64 v[92:93], 8, v[108:109]
	v_cvt_pk_bf16_f32 v89, v94, v95
	v_lshl_add_u64 v[92:93], v[146:147], 0, v[92:93]
	v_cvt_pk_bf16_f32 v90, v90, v91
	v_cvt_pk_bf16_f32 v91, v98, v99
	global_store_dwordx4 v[92:93], v[88:91], off
	s_nop 1
	v_lshlrev_b64 v[88:89], 8, v[186:187]
	v_lshl_add_u64 v[88:89], v[148:149], 0, v[88:89]
	v_mov_b64_e32 v[90:91], v[240:241]
	s_nop 0
	v_mul_f32_e32 v90, v104, v90
	v_mov_b64_e32 v[88:89], v[242:243]
	v_mul_f32_e32 v94, v162, v90
	v_mul_f32_e32 v90, v104, v91
	v_mul_f32_e32 v95, v163, v90
	s_nop 0
	v_mul_f32_e32 v88, v104, v88
	v_mul_f32_e32 v98, v160, v88
	v_mul_f32_e32 v88, v104, v89
	v_mul_f32_e32 v99, v161, v88
	v_lshlrev_b64 v[88:89], 7, v[186:187]
	v_or_b32_e32 v88, v88, v122
	v_lshl_add_u64 v[90:91], s[16:17], 0, v[88:89]
	v_lshl_add_u64 v[88:89], s[26:27], 0, v[88:89]
	v_mov_b64_e32 v[90:91], v[244:245]
	s_nop 0
	v_mov_b64_e32 v[88:89], v[246:247]
	s_nop 0
	v_mul_f32_e32 v92, v98, v88
	v_mul_f32_e32 v93, v99, v89
	v_fma_f32 v92, v94, v90, -v92
	v_fma_f32 v93, v95, v91, -v93
	v_mul_f32_e32 v88, v94, v88
	v_cvt_pk_bf16_f32 v100, v92, v93
	v_lshl_add_u64 v[92:93], v[96:97], 0, v[120:121]
	v_fmac_f32_e32 v88, v98, v90
	v_mul_f32_e32 v89, v95, v89
	global_store_dword v[92:93], v100, off offset:256
	v_fmac_f32_e32 v89, v99, v91
	v_cvt_pk_bf16_f32 v88, v88, v89
	global_store_dword v[92:93], v88, off offset:320
	v_add_u32_e32 v88, s31, v205
	ds_read_b128 v[88:91], v88
	s_waitcnt lgkmcnt(0)
	v_mov_b32_e32 v92, v89
	v_mov_b32_e32 v93, v90
	v_mov_b32_e32 v89, v91
	v_pk_add_f32 v[88:89], v[92:93], v[88:89]
	s_nop 0
	v_add_f32_e32 v90, v88, v89
	v_lshl_add_u64 v[88:89], v[182:183], 2, s[24:25]
	global_load_dword v88, v[88:89], off
	v_lshlrev_b64 v[248:249], 8, v[182:183]
	v_lshl_add_u64 v[248:249], v[148:149], 0, v[248:249]
	global_load_dwordx2 v[240:241], v[248:249], off
	global_load_dwordx2 v[242:243], v[248:249], off offset:128
	v_lshlrev_b64 v[248:249], 7, v[182:183]
	v_lshlrev_b32_e32 v250, 2, v144
	v_or_b32_e32 v248, v248, v250
	v_lshl_add_u64 v[250:251], s[16:17], 0, v[248:249]
	v_lshl_add_u64 v[248:249], s[26:27], 0, v[248:249]
	global_load_dwordx2 v[244:245], v[250:251], off
	global_load_dwordx2 v[246:247], v[248:249], off
	s_waitcnt vmcnt(0)
	v_add_f32_e32 v88, v88, v90
	v_fmamk_f32 v88, v88, 0x3baaaaab, v197
	v_cmp_gt_f32_e32 vcc, s36, v88
	v_mul_f32_e32 v89, 0x4f800000, v88
	s_nop 0
	v_cndmask_b32_e32 v88, v88, v89, vcc
	v_sqrt_f32_e32 v89, v88
	s_nop 0
	v_add_u32_e32 v90, -1, v89
	v_fma_f32 v91, -v90, v89, v88
	v_cmp_ge_f32_e64 s[12:13], 0, v91
	v_add_u32_e32 v91, 1, v89
	s_nop 0
	v_cndmask_b32_e64 v90, v89, v90, s[12:13]
	v_fma_f32 v89, -v91, v89, v88
	v_cmp_lt_f32_e64 s[12:13], 0, v89
	s_nop 1
	v_cndmask_b32_e64 v89, v90, v91, s[12:13]
	v_mul_f32_e32 v90, 0x37800000, v89
	v_cndmask_b32_e32 v89, v89, v90, vcc
	v_cmp_class_f32_e32 vcc, v88, v198
	s_nop 1
	v_cndmask_b32_e32 v88, v89, v88, vcc
	v_div_scale_f32 v89, s[2:3], v88, v88, 1.0
	v_rcp_f32_e32 v90, v89
	s_nop 0
	v_fma_f32 v91, -v89, v90, 1.0
	v_fmac_f32_e32 v90, v91, v90
	v_div_scale_f32 v91, vcc, 1.0, v88, 1.0
	v_mul_f32_e32 v92, v91, v90
	v_fma_f32 v93, -v89, v92, v91
	v_fmac_f32_e32 v92, v93, v90
	v_fma_f32 v89, -v89, v92, v91
	v_div_fmas_f32 v89, v89, v90, v92
	v_div_fixup_f32 v88, v89, v88, 1.0
	v_ashrrev_i32_e32 v89, 8, v182
	v_and_b32_e32 v89, -16, v89
	v_add_u32_e32 v92, s95, v89
	v_mul_f32_e32 v90, v184, v88
	v_ashrrev_i32_e32 v93, 31, v92
	v_lshlrev_b64 v[92:93], 12, v[92:93]
	v_pk_mul_f32 v[76:77], v[76:77], v[90:91] op_sel_hi:[1,0]
	v_pk_mul_f32 v[72:73], v[72:73], v[90:91] op_sel_hi:[1,0]
	v_and_or_b32 v92, v182, s77, v92
	v_pk_mul_f32 v[78:79], v[78:79], v[90:91] op_sel_hi:[1,0]
	v_pk_mul_f32 v[76:77], v[84:85], v[76:77]
	v_pk_mul_f32 v[74:75], v[74:75], v[90:91] op_sel_hi:[1,0]
	v_pk_mul_f32 v[72:73], v[80:81], v[72:73]
	v_pk_mul_f32 v[78:79], v[86:87], v[78:79]
	v_pk_mul_f32 v[90:91], v[82:83], v[74:75]
	v_cvt_pk_bf16_f32 v74, v76, v77
	v_cvt_pk_bf16_f32 v75, v78, v79
	v_cvt_pk_bf16_f32 v76, v72, v73
	v_mad_u64_u32 v[72:73], s[2:3], v92, s35, v[128:129]
	v_mad_i32_i24 v73, v93, s35, v73
	v_lshl_add_u64 v[78:79], v[72:73], 0, v[176:177]
	v_cvt_pk_bf16_f32 v77, v90, v91
	global_store_dwordx4 v[78:79], v[74:77], off
	s_nop 1
	v_pk_mul_f32 v[74:75], v[66:67], v[184:185] op_sel_hi:[1,0]
	v_pk_mul_f32 v[66:67], v[64:65], v[184:185] op_sel_hi:[1,0]
	v_cvt_pk_bf16_f32 v64, v68, v69
	v_lshlrev_b64 v[68:69], 8, v[92:93]
	v_cvt_pk_bf16_f32 v65, v70, v71
	v_lshl_add_u64 v[68:69], v[146:147], 0, v[68:69]
	v_cvt_pk_bf16_f32 v66, v66, v67
	v_cvt_pk_bf16_f32 v67, v74, v75
	global_store_dwordx4 v[68:69], v[64:67], off
	s_nop 1
	v_lshlrev_b64 v[64:65], 8, v[182:183]
	v_lshl_add_u64 v[64:65], v[148:149], 0, v[64:65]
	v_mov_b64_e32 v[66:67], v[240:241]
	s_nop 0
	v_mul_f32_e32 v66, v88, v66
	v_mov_b64_e32 v[64:65], v[242:243]
	v_mul_f32_e32 v70, v162, v66
	v_mul_f32_e32 v66, v88, v67
	v_mul_f32_e32 v71, v163, v66
	s_nop 0
	v_mul_f32_e32 v64, v88, v64
	v_mul_f32_e32 v74, v160, v64
	v_mul_f32_e32 v64, v88, v65
	v_mul_f32_e32 v75, v161, v64
	v_lshlrev_b64 v[64:65], 7, v[182:183]
	v_or_b32_e32 v64, v64, v122
	v_lshl_add_u64 v[66:67], s[16:17], 0, v[64:65]
	v_lshl_add_u64 v[64:65], s[26:27], 0, v[64:65]
	v_mov_b64_e32 v[66:67], v[244:245]
	s_nop 0
	v_mov_b64_e32 v[64:65], v[246:247]
	s_nop 0
	v_mul_f32_e32 v68, v74, v64
	v_mul_f32_e32 v69, v75, v65
	v_fma_f32 v68, v70, v66, -v68
	v_fma_f32 v69, v71, v67, -v69
	v_mul_f32_e32 v64, v70, v64
	v_cvt_pk_bf16_f32 v76, v68, v69
	v_lshl_add_u64 v[68:69], v[72:73], 0, v[120:121]
	v_fmac_f32_e32 v64, v74, v66
	v_mul_f32_e32 v65, v71, v65
	global_store_dword v[68:69], v76, off offset:256
	v_fmac_f32_e32 v65, v75, v67
	v_cvt_pk_bf16_f32 v64, v64, v65
	global_store_dword v[68:69], v64, off offset:320
	v_add_u32_e32 v64, s31, v207
	ds_read_b128 v[64:67], v64
	s_waitcnt lgkmcnt(0)
	v_mov_b32_e32 v68, v65
	v_mov_b32_e32 v69, v66
	v_mov_b32_e32 v65, v67
	v_pk_add_f32 v[64:65], v[68:69], v[64:65]
	s_nop 0
	v_add_f32_e32 v66, v64, v65
	v_lshl_add_u64 v[64:65], v[174:175], 2, s[24:25]
	global_load_dword v64, v[64:65], off
	v_lshlrev_b64 v[248:249], 8, v[174:175]
	v_lshl_add_u64 v[248:249], v[148:149], 0, v[248:249]
	global_load_dwordx2 v[240:241], v[248:249], off
	global_load_dwordx2 v[242:243], v[248:249], off offset:128
	v_lshlrev_b64 v[248:249], 7, v[174:175]
	v_lshlrev_b32_e32 v250, 2, v144
	v_or_b32_e32 v248, v248, v250
	v_lshl_add_u64 v[250:251], s[16:17], 0, v[248:249]
	v_lshl_add_u64 v[248:249], s[26:27], 0, v[248:249]
	global_load_dwordx2 v[244:245], v[250:251], off
	global_load_dwordx2 v[246:247], v[248:249], off
	s_waitcnt vmcnt(0)
	v_add_f32_e32 v64, v64, v66
	v_fmamk_f32 v64, v64, 0x3baaaaab, v197
	v_cmp_gt_f32_e32 vcc, s36, v64
	v_mul_f32_e32 v65, 0x4f800000, v64
	s_nop 0
	v_cndmask_b32_e32 v64, v64, v65, vcc
	v_sqrt_f32_e32 v65, v64
	s_nop 0
	v_add_u32_e32 v66, -1, v65
	v_fma_f32 v67, -v66, v65, v64
	v_cmp_ge_f32_e64 s[12:13], 0, v67
	v_add_u32_e32 v67, 1, v65
	s_nop 0
	v_cndmask_b32_e64 v66, v65, v66, s[12:13]
	v_fma_f32 v65, -v67, v65, v64
	v_cmp_lt_f32_e64 s[12:13], 0, v65
	s_nop 1
	v_cndmask_b32_e64 v65, v66, v67, s[12:13]
	v_mul_f32_e32 v66, 0x37800000, v65
	v_cndmask_b32_e32 v65, v65, v66, vcc
	v_cmp_class_f32_e32 vcc, v64, v198
	s_nop 1
	v_cndmask_b32_e32 v64, v65, v64, vcc
	v_div_scale_f32 v65, s[2:3], v64, v64, 1.0
	v_rcp_f32_e32 v66, v65
	s_nop 0
	v_fma_f32 v67, -v65, v66, 1.0
	v_fmac_f32_e32 v66, v67, v66
	v_div_scale_f32 v67, vcc, 1.0, v64, 1.0
	v_mul_f32_e32 v68, v67, v66
	v_fma_f32 v69, -v65, v68, v67
	v_fmac_f32_e32 v68, v69, v66
	v_fma_f32 v65, -v65, v68, v67
	v_div_fmas_f32 v65, v65, v66, v68
	v_div_fixup_f32 v64, v65, v64, 1.0
	v_ashrrev_i32_e32 v65, 8, v174
	v_and_b32_e32 v65, -16, v65
	v_add_u32_e32 v68, s95, v65
	v_mul_f32_e32 v66, v180, v64
	v_ashrrev_i32_e32 v69, 31, v68
	v_lshlrev_b64 v[68:69], 12, v[68:69]
	v_pk_mul_f32 v[60:61], v[60:61], v[66:67] op_sel_hi:[1,0]
	v_pk_mul_f32 v[56:57], v[56:57], v[66:67] op_sel_hi:[1,0]
	v_and_or_b32 v68, v174, s4, v68
	v_pk_mul_f32 v[62:63], v[62:63], v[66:67] op_sel_hi:[1,0]
	v_pk_mul_f32 v[60:61], v[84:85], v[60:61]
	v_pk_mul_f32 v[58:59], v[58:59], v[66:67] op_sel_hi:[1,0]
	v_pk_mul_f32 v[56:57], v[80:81], v[56:57]
	v_pk_mul_f32 v[62:63], v[86:87], v[62:63]
	v_pk_mul_f32 v[66:67], v[82:83], v[58:59]
	v_cvt_pk_bf16_f32 v58, v60, v61
	v_cvt_pk_bf16_f32 v59, v62, v63
	v_cvt_pk_bf16_f32 v60, v56, v57
	v_mad_u64_u32 v[56:57], s[2:3], v68, s35, v[128:129]
	v_mad_i32_i24 v57, v69, s35, v57
	v_lshl_add_u64 v[62:63], v[56:57], 0, v[176:177]
	v_cvt_pk_bf16_f32 v61, v66, v67
	global_store_dwordx4 v[62:63], v[58:61], off
	s_nop 1
	v_pk_mul_f32 v[58:59], v[50:51], v[180:181] op_sel_hi:[1,0]
	v_pk_mul_f32 v[50:51], v[48:49], v[180:181] op_sel_hi:[1,0]
	v_cvt_pk_bf16_f32 v48, v52, v53
	v_lshlrev_b64 v[52:53], 8, v[68:69]
	v_cvt_pk_bf16_f32 v49, v54, v55
	v_lshl_add_u64 v[52:53], v[146:147], 0, v[52:53]
	v_cvt_pk_bf16_f32 v50, v50, v51
	v_cvt_pk_bf16_f32 v51, v58, v59
	global_store_dwordx4 v[52:53], v[48:51], off
	s_nop 1
	v_lshlrev_b64 v[48:49], 8, v[174:175]
	v_lshl_add_u64 v[48:49], v[148:149], 0, v[48:49]
	v_mov_b64_e32 v[50:51], v[240:241]
	s_nop 0
	v_mul_f32_e32 v50, v64, v50
	v_mov_b64_e32 v[48:49], v[242:243]
	v_mul_f32_e32 v54, v162, v50
	v_mul_f32_e32 v50, v64, v51
	v_mul_f32_e32 v55, v163, v50
	s_nop 0
	v_mul_f32_e32 v48, v64, v48
	v_mul_f32_e32 v58, v160, v48
	v_mul_f32_e32 v48, v64, v49
	v_mul_f32_e32 v59, v161, v48
	v_lshlrev_b64 v[48:49], 7, v[174:175]
	v_or_b32_e32 v48, v48, v122
	v_lshl_add_u64 v[50:51], s[16:17], 0, v[48:49]
	v_lshl_add_u64 v[48:49], s[26:27], 0, v[48:49]
	v_mov_b64_e32 v[50:51], v[244:245]
	s_nop 0
	v_mov_b64_e32 v[48:49], v[246:247]
	s_nop 0
	v_mul_f32_e32 v52, v58, v48
	v_mul_f32_e32 v53, v59, v49
	v_fma_f32 v52, v54, v50, -v52
	v_fma_f32 v53, v55, v51, -v53
	v_mul_f32_e32 v48, v54, v48
	v_cvt_pk_bf16_f32 v60, v52, v53
	v_lshl_add_u64 v[52:53], v[56:57], 0, v[120:121]
	v_fmac_f32_e32 v48, v58, v50
	v_mul_f32_e32 v49, v55, v49
	global_store_dword v[52:53], v60, off offset:256
	v_fmac_f32_e32 v49, v59, v51
	v_cvt_pk_bf16_f32 v48, v48, v49
	global_store_dword v[52:53], v48, off offset:320
	v_add_u32_e32 v48, s31, v209
	ds_read_b128 v[48:51], v48
	s_waitcnt lgkmcnt(0)
	v_mov_b32_e32 v52, v49
	v_mov_b32_e32 v53, v50
	v_mov_b32_e32 v49, v51
	v_pk_add_f32 v[48:49], v[52:53], v[48:49]
	s_nop 0
	v_add_f32_e32 v50, v48, v49
	v_lshl_add_u64 v[48:49], v[170:171], 2, s[24:25]
	global_load_dword v48, v[48:49], off
	v_lshlrev_b64 v[248:249], 8, v[170:171]
	v_lshl_add_u64 v[248:249], v[148:149], 0, v[248:249]
	global_load_dwordx2 v[240:241], v[248:249], off
	global_load_dwordx2 v[242:243], v[248:249], off offset:128
	v_lshlrev_b64 v[248:249], 7, v[170:171]
	v_lshlrev_b32_e32 v250, 2, v144
	v_or_b32_e32 v248, v248, v250
	v_lshl_add_u64 v[250:251], s[16:17], 0, v[248:249]
	v_lshl_add_u64 v[248:249], s[26:27], 0, v[248:249]
	global_load_dwordx2 v[244:245], v[250:251], off
	global_load_dwordx2 v[246:247], v[248:249], off
	s_waitcnt vmcnt(0)
	v_add_f32_e32 v48, v48, v50
	v_fmamk_f32 v48, v48, 0x3baaaaab, v197
	v_cmp_gt_f32_e32 vcc, s36, v48
	v_mul_f32_e32 v49, 0x4f800000, v48
	s_nop 0
	v_cndmask_b32_e32 v48, v48, v49, vcc
	v_sqrt_f32_e32 v49, v48
	s_nop 0
	v_add_u32_e32 v50, -1, v49
	v_fma_f32 v51, -v50, v49, v48
	v_cmp_ge_f32_e64 s[12:13], 0, v51
	v_add_u32_e32 v51, 1, v49
	s_nop 0
	v_cndmask_b32_e64 v50, v49, v50, s[12:13]
	v_fma_f32 v49, -v51, v49, v48
	v_cmp_lt_f32_e64 s[12:13], 0, v49
	s_nop 1
	v_cndmask_b32_e64 v49, v50, v51, s[12:13]
	v_mul_f32_e32 v50, 0x37800000, v49
	v_cndmask_b32_e32 v49, v49, v50, vcc
	v_cmp_class_f32_e32 vcc, v48, v198
	s_nop 1
	v_cndmask_b32_e32 v48, v49, v48, vcc
	v_div_scale_f32 v49, s[2:3], v48, v48, 1.0
	v_rcp_f32_e32 v50, v49
	s_nop 0
	v_fma_f32 v51, -v49, v50, 1.0
	v_fmac_f32_e32 v50, v51, v50
	v_div_scale_f32 v51, vcc, 1.0, v48, 1.0
	v_mul_f32_e32 v52, v51, v50
	v_fma_f32 v53, -v49, v52, v51
	v_fmac_f32_e32 v52, v53, v50
	v_fma_f32 v49, -v49, v52, v51
	v_div_fmas_f32 v49, v49, v50, v52
	v_div_fixup_f32 v48, v49, v48, 1.0
	v_ashrrev_i32_e32 v49, 8, v170
	v_and_b32_e32 v49, -16, v49
	v_add_u32_e32 v52, s95, v49
	v_mul_f32_e32 v50, v172, v48
	v_ashrrev_i32_e32 v53, 31, v52
	v_lshlrev_b64 v[52:53], 12, v[52:53]
	v_pk_mul_f32 v[44:45], v[44:45], v[50:51] op_sel_hi:[1,0]
	v_pk_mul_f32 v[40:41], v[40:41], v[50:51] op_sel_hi:[1,0]
	v_and_or_b32 v52, v170, s74, v52
	v_pk_mul_f32 v[46:47], v[46:47], v[50:51] op_sel_hi:[1,0]
	v_pk_mul_f32 v[44:45], v[84:85], v[44:45]
	v_pk_mul_f32 v[42:43], v[42:43], v[50:51] op_sel_hi:[1,0]
	v_pk_mul_f32 v[40:41], v[80:81], v[40:41]
	v_pk_mul_f32 v[46:47], v[86:87], v[46:47]
	v_pk_mul_f32 v[50:51], v[82:83], v[42:43]
	v_cvt_pk_bf16_f32 v42, v44, v45
	v_cvt_pk_bf16_f32 v43, v46, v47
	v_cvt_pk_bf16_f32 v44, v40, v41
	v_mad_u64_u32 v[40:41], s[2:3], v52, s35, v[128:129]
	v_mad_i32_i24 v41, v53, s35, v41
	v_lshl_add_u64 v[46:47], v[40:41], 0, v[176:177]
	v_cvt_pk_bf16_f32 v45, v50, v51
	global_store_dwordx4 v[46:47], v[42:45], off
	s_nop 1
	v_pk_mul_f32 v[42:43], v[34:35], v[172:173] op_sel_hi:[1,0]
	v_pk_mul_f32 v[34:35], v[32:33], v[172:173] op_sel_hi:[1,0]
	v_cvt_pk_bf16_f32 v32, v36, v37
	v_lshlrev_b64 v[36:37], 8, v[52:53]
	v_cvt_pk_bf16_f32 v33, v38, v39
	v_lshl_add_u64 v[36:37], v[146:147], 0, v[36:37]
	v_cvt_pk_bf16_f32 v34, v34, v35
	v_cvt_pk_bf16_f32 v35, v42, v43
	global_store_dwordx4 v[36:37], v[32:35], off
	s_nop 1
	v_lshlrev_b64 v[32:33], 8, v[170:171]
	v_lshl_add_u64 v[32:33], v[148:149], 0, v[32:33]
	v_mov_b64_e32 v[34:35], v[240:241]
	s_nop 0
	v_mul_f32_e32 v34, v48, v34
	v_mov_b64_e32 v[32:33], v[242:243]
	v_mul_f32_e32 v38, v162, v34
	v_mul_f32_e32 v34, v48, v35
	v_mul_f32_e32 v39, v163, v34
	s_nop 0
	v_mul_f32_e32 v32, v48, v32
	v_mul_f32_e32 v42, v160, v32
	v_mul_f32_e32 v32, v48, v33
	v_mul_f32_e32 v43, v161, v32
	v_lshlrev_b64 v[32:33], 7, v[170:171]
	v_or_b32_e32 v32, v32, v122
	v_lshl_add_u64 v[34:35], s[16:17], 0, v[32:33]
	v_lshl_add_u64 v[32:33], s[26:27], 0, v[32:33]
	v_mov_b64_e32 v[34:35], v[244:245]
	s_nop 0
	v_mov_b64_e32 v[32:33], v[246:247]
	s_nop 0
	v_mul_f32_e32 v36, v42, v32
	v_mul_f32_e32 v37, v43, v33
	v_fma_f32 v36, v38, v34, -v36
	v_fma_f32 v37, v39, v35, -v37
	v_mul_f32_e32 v32, v38, v32
	v_cvt_pk_bf16_f32 v44, v36, v37
	v_lshl_add_u64 v[36:37], v[40:41], 0, v[120:121]
	v_fmac_f32_e32 v32, v42, v34
	v_mul_f32_e32 v33, v39, v33
	global_store_dword v[36:37], v44, off offset:256
	v_fmac_f32_e32 v33, v43, v35
	v_cvt_pk_bf16_f32 v32, v32, v33
	global_store_dword v[36:37], v32, off offset:320
	v_add_u32_e32 v32, s31, v211
	ds_read_b128 v[32:35], v32
	s_waitcnt lgkmcnt(0)
	v_mov_b32_e32 v36, v33
	v_mov_b32_e32 v37, v34
	v_mov_b32_e32 v33, v35
	v_pk_add_f32 v[32:33], v[36:37], v[32:33]
	s_nop 0
	v_add_f32_e32 v34, v32, v33
	v_lshl_add_u64 v[32:33], v[166:167], 2, s[24:25]
	global_load_dword v32, v[32:33], off
	v_lshlrev_b64 v[248:249], 8, v[166:167]
	v_lshl_add_u64 v[248:249], v[148:149], 0, v[248:249]
	global_load_dwordx2 v[240:241], v[248:249], off
	global_load_dwordx2 v[242:243], v[248:249], off offset:128
	v_lshlrev_b64 v[248:249], 7, v[166:167]
	v_lshlrev_b32_e32 v250, 2, v144
	v_or_b32_e32 v248, v248, v250
	v_lshl_add_u64 v[250:251], s[16:17], 0, v[248:249]
	v_lshl_add_u64 v[248:249], s[26:27], 0, v[248:249]
	global_load_dwordx2 v[244:245], v[250:251], off
	global_load_dwordx2 v[246:247], v[248:249], off
	s_waitcnt vmcnt(0)
	v_add_f32_e32 v32, v32, v34
	v_fmamk_f32 v32, v32, 0x3baaaaab, v197
	v_cmp_gt_f32_e32 vcc, s36, v32
	v_mul_f32_e32 v33, 0x4f800000, v32
	s_nop 0
	v_cndmask_b32_e32 v32, v32, v33, vcc
	v_sqrt_f32_e32 v33, v32
	s_nop 0
	v_add_u32_e32 v34, -1, v33
	v_fma_f32 v35, -v34, v33, v32
	v_cmp_ge_f32_e64 s[12:13], 0, v35
	v_add_u32_e32 v35, 1, v33
	s_nop 0
	v_cndmask_b32_e64 v34, v33, v34, s[12:13]
	v_fma_f32 v33, -v35, v33, v32
	v_cmp_lt_f32_e64 s[12:13], 0, v33
	s_nop 1
	v_cndmask_b32_e64 v33, v34, v35, s[12:13]
	v_mul_f32_e32 v34, 0x37800000, v33
	v_cndmask_b32_e32 v33, v33, v34, vcc
	v_cmp_class_f32_e32 vcc, v32, v198
	s_nop 1
	v_cndmask_b32_e32 v32, v33, v32, vcc
	v_div_scale_f32 v33, s[2:3], v32, v32, 1.0
	v_rcp_f32_e32 v34, v33
	s_nop 0
	v_fma_f32 v35, -v33, v34, 1.0
	v_fmac_f32_e32 v34, v35, v34
	v_div_scale_f32 v35, vcc, 1.0, v32, 1.0
	v_mul_f32_e32 v36, v35, v34
	v_fma_f32 v37, -v33, v36, v35
	v_fmac_f32_e32 v36, v37, v34
	v_fma_f32 v33, -v33, v36, v35
	v_div_fmas_f32 v33, v33, v34, v36
	v_div_fixup_f32 v32, v33, v32, 1.0
	v_ashrrev_i32_e32 v33, 8, v166
	v_and_b32_e32 v33, -16, v33
	v_add_u32_e32 v36, s95, v33
	v_mul_f32_e32 v34, v168, v32
	v_ashrrev_i32_e32 v37, 31, v36
	v_lshlrev_b64 v[36:37], 12, v[36:37]
	v_pk_mul_f32 v[28:29], v[28:29], v[34:35] op_sel_hi:[1,0]
	v_pk_mul_f32 v[24:25], v[24:25], v[34:35] op_sel_hi:[1,0]
	v_and_or_b32 v36, v166, s75, v36
	v_pk_mul_f32 v[30:31], v[30:31], v[34:35] op_sel_hi:[1,0]
	v_pk_mul_f32 v[28:29], v[84:85], v[28:29]
	v_pk_mul_f32 v[26:27], v[26:27], v[34:35] op_sel_hi:[1,0]
	v_pk_mul_f32 v[24:25], v[80:81], v[24:25]
	v_pk_mul_f32 v[30:31], v[86:87], v[30:31]
	v_pk_mul_f32 v[34:35], v[82:83], v[26:27]
	v_cvt_pk_bf16_f32 v26, v28, v29
	v_cvt_pk_bf16_f32 v27, v30, v31
	v_cvt_pk_bf16_f32 v28, v24, v25
	v_mad_u64_u32 v[24:25], s[2:3], v36, s35, v[128:129]
	v_mad_i32_i24 v25, v37, s35, v25
	v_lshl_add_u64 v[30:31], v[24:25], 0, v[176:177]
	v_cvt_pk_bf16_f32 v29, v34, v35
	global_store_dwordx4 v[30:31], v[26:29], off
	s_nop 1
	v_pk_mul_f32 v[26:27], v[18:19], v[168:169] op_sel_hi:[1,0]
	v_pk_mul_f32 v[18:19], v[16:17], v[168:169] op_sel_hi:[1,0]
	v_cvt_pk_bf16_f32 v16, v20, v21
	v_lshlrev_b64 v[20:21], 8, v[36:37]
	v_cvt_pk_bf16_f32 v17, v22, v23
	v_lshl_add_u64 v[20:21], v[146:147], 0, v[20:21]
	v_cvt_pk_bf16_f32 v18, v18, v19
	v_cvt_pk_bf16_f32 v19, v26, v27
	global_store_dwordx4 v[20:21], v[16:19], off
	s_nop 1
	v_lshlrev_b64 v[16:17], 8, v[166:167]
	v_lshl_add_u64 v[16:17], v[148:149], 0, v[16:17]
	v_mov_b64_e32 v[18:19], v[240:241]
	s_nop 0
	v_mul_f32_e32 v18, v32, v18
	v_mov_b64_e32 v[16:17], v[242:243]
	v_mul_f32_e32 v22, v162, v18
	v_mul_f32_e32 v18, v32, v19
	v_mul_f32_e32 v23, v163, v18
	s_nop 0
	v_mul_f32_e32 v16, v32, v16
	v_mul_f32_e32 v26, v160, v16
	v_mul_f32_e32 v16, v32, v17
	v_mul_f32_e32 v27, v161, v16
	v_lshlrev_b64 v[16:17], 7, v[166:167]
	v_or_b32_e32 v16, v16, v122
	v_lshl_add_u64 v[18:19], s[16:17], 0, v[16:17]
	v_lshl_add_u64 v[16:17], s[26:27], 0, v[16:17]
	v_mov_b64_e32 v[18:19], v[244:245]
	s_nop 0
	v_mov_b64_e32 v[16:17], v[246:247]
	s_nop 0
	v_mul_f32_e32 v20, v26, v16
	v_mul_f32_e32 v21, v27, v17
	v_fma_f32 v20, v22, v18, -v20
	v_fma_f32 v21, v23, v19, -v21
	v_mul_f32_e32 v16, v22, v16
	v_cvt_pk_bf16_f32 v28, v20, v21
	v_lshl_add_u64 v[20:21], v[24:25], 0, v[120:121]
	v_fmac_f32_e32 v16, v26, v18
	v_mul_f32_e32 v17, v23, v17
	global_store_dword v[20:21], v28, off offset:256
	v_fmac_f32_e32 v17, v27, v19
	v_cvt_pk_bf16_f32 v16, v16, v17
	global_store_dword v[20:21], v16, off offset:320
	v_add_u32_e32 v16, s31, v213
	ds_read_b128 v[16:19], v16
	s_waitcnt lgkmcnt(0)
	v_mov_b32_e32 v20, v17
	v_mov_b32_e32 v21, v18
	v_mov_b32_e32 v17, v19
	v_pk_add_f32 v[16:17], v[20:21], v[16:17]
	s_nop 0
	v_add_f32_e32 v18, v16, v17
	v_lshl_add_u64 v[16:17], v[158:159], 2, s[24:25]
	global_load_dword v16, v[16:17], off
	v_lshlrev_b64 v[248:249], 8, v[158:159]
	v_lshl_add_u64 v[248:249], v[148:149], 0, v[248:249]
	global_load_dwordx2 v[240:241], v[248:249], off
	global_load_dwordx2 v[242:243], v[248:249], off offset:128
	v_lshlrev_b64 v[248:249], 7, v[158:159]
	v_lshlrev_b32_e32 v250, 2, v144
	v_or_b32_e32 v248, v248, v250
	v_lshl_add_u64 v[250:251], s[16:17], 0, v[248:249]
	v_lshl_add_u64 v[248:249], s[26:27], 0, v[248:249]
	global_load_dwordx2 v[244:245], v[250:251], off
	global_load_dwordx2 v[246:247], v[248:249], off
	s_waitcnt vmcnt(0)
	v_add_f32_e32 v16, v16, v18
	v_fmamk_f32 v16, v16, 0x3baaaaab, v197
	v_cmp_gt_f32_e32 vcc, s36, v16
	v_mul_f32_e32 v17, 0x4f800000, v16
	s_nop 0
	v_cndmask_b32_e32 v16, v16, v17, vcc
	v_sqrt_f32_e32 v17, v16
	s_nop 0
	v_add_u32_e32 v18, -1, v17
	v_fma_f32 v19, -v18, v17, v16
	v_cmp_ge_f32_e64 s[12:13], 0, v19
	v_add_u32_e32 v19, 1, v17
	s_nop 0
	v_cndmask_b32_e64 v18, v17, v18, s[12:13]
	v_fma_f32 v17, -v19, v17, v16
	v_cmp_lt_f32_e64 s[12:13], 0, v17
	s_nop 1
	v_cndmask_b32_e64 v17, v18, v19, s[12:13]
	v_mul_f32_e32 v18, 0x37800000, v17
	v_cndmask_b32_e32 v17, v17, v18, vcc
	v_cmp_class_f32_e32 vcc, v16, v198
	s_mov_b64 s[12:13], -1
	s_nop 0
	v_cndmask_b32_e32 v16, v17, v16, vcc
	v_div_scale_f32 v17, s[2:3], v16, v16, 1.0
	v_rcp_f32_e32 v18, v17
	s_nop 0
	v_fma_f32 v19, -v17, v18, 1.0
	v_fmac_f32_e32 v18, v19, v18
	v_div_scale_f32 v19, vcc, 1.0, v16, 1.0
	v_mul_f32_e32 v20, v19, v18
	v_fma_f32 v21, -v17, v20, v19
	v_fmac_f32_e32 v20, v21, v18
	v_fma_f32 v17, -v17, v20, v19
	v_div_fmas_f32 v17, v17, v18, v20
	v_div_fixup_f32 v16, v17, v16, 1.0
	v_ashrrev_i32_e32 v17, 8, v158
	v_and_b32_e32 v17, -16, v17
	v_add_u32_e32 v20, s95, v17
	v_mul_f32_e32 v18, v164, v16
	v_ashrrev_i32_e32 v21, 31, v20
	v_lshlrev_b64 v[20:21], 12, v[20:21]
	v_pk_mul_f32 v[12:13], v[12:13], v[18:19] op_sel_hi:[1,0]
	v_pk_mul_f32 v[8:9], v[8:9], v[18:19] op_sel_hi:[1,0]
	v_and_or_b32 v20, v158, s77, v20
	v_pk_mul_f32 v[14:15], v[14:15], v[18:19] op_sel_hi:[1,0]
	v_pk_mul_f32 v[12:13], v[84:85], v[12:13]
	v_pk_mul_f32 v[10:11], v[10:11], v[18:19] op_sel_hi:[1,0]
	v_pk_mul_f32 v[8:9], v[80:81], v[8:9]
	v_pk_mul_f32 v[14:15], v[86:87], v[14:15]
	v_pk_mul_f32 v[18:19], v[82:83], v[10:11]
	v_cvt_pk_bf16_f32 v10, v12, v13
	v_cvt_pk_bf16_f32 v11, v14, v15
	v_cvt_pk_bf16_f32 v12, v8, v9
	v_mad_u64_u32 v[8:9], s[2:3], v20, s35, v[128:129]
	v_mad_i32_i24 v9, v21, s35, v9
	v_lshl_add_u64 v[14:15], v[8:9], 0, v[176:177]
	v_cvt_pk_bf16_f32 v13, v18, v19
	global_store_dwordx4 v[14:15], v[10:13], off
	s_andn2_b64 vcc, exec, s[10:11]
	s_nop 0
	v_pk_mul_f32 v[10:11], v[2:3], v[164:165] op_sel_hi:[1,0]
	v_pk_mul_f32 v[2:3], v[0:1], v[164:165] op_sel_hi:[1,0]
	v_cvt_pk_bf16_f32 v0, v4, v5
	v_lshlrev_b64 v[4:5], 8, v[20:21]
	v_cvt_pk_bf16_f32 v1, v6, v7
	v_lshl_add_u64 v[4:5], v[146:147], 0, v[4:5]
	v_cvt_pk_bf16_f32 v2, v2, v3
	v_cvt_pk_bf16_f32 v3, v10, v11
	global_store_dwordx4 v[4:5], v[0:3], off
	s_nop 1
	v_lshlrev_b64 v[0:1], 8, v[158:159]
	v_lshl_add_u64 v[0:1], v[148:149], 0, v[0:1]
	v_mov_b64_e32 v[2:3], v[240:241]
	s_nop 0
	v_mul_f32_e32 v2, v16, v2
	v_mov_b64_e32 v[0:1], v[242:243]
	v_mul_f32_e32 v6, v162, v2
	v_mul_f32_e32 v2, v16, v3
	v_mul_f32_e32 v7, v163, v2
	s_nop 0
	v_mul_f32_e32 v0, v16, v0
	v_mul_f32_e32 v10, v160, v0
	v_mul_f32_e32 v0, v16, v1
	v_mul_f32_e32 v11, v161, v0
	v_lshlrev_b64 v[0:1], 7, v[158:159]
	v_or_b32_e32 v0, v0, v122
	v_lshl_add_u64 v[2:3], s[16:17], 0, v[0:1]
	v_lshl_add_u64 v[0:1], s[26:27], 0, v[0:1]
	v_mov_b64_e32 v[2:3], v[244:245]
	s_nop 0
	v_mov_b64_e32 v[0:1], v[246:247]
	s_nop 0
	v_mul_f32_e32 v4, v10, v0
	v_mul_f32_e32 v5, v11, v1
	v_fma_f32 v4, v6, v2, -v4
	v_fma_f32 v5, v7, v3, -v5
	v_mul_f32_e32 v0, v6, v0
	v_cvt_pk_bf16_f32 v12, v4, v5
	v_lshl_add_u64 v[4:5], v[8:9], 0, v[120:121]
	v_fmac_f32_e32 v0, v10, v2
	v_mul_f32_e32 v1, v7, v1
	global_store_dword v[4:5], v12, off offset:256
	v_fmac_f32_e32 v1, v11, v3
	v_cvt_pk_bf16_f32 v0, v0, v1
	global_store_dword v[4:5], v0, off offset:320
	s_cbranch_vccnz .LBB0_629
	s_andn2_b64 vcc, exec, s[18:19]
	s_cbranch_vccnz .LBB0_628
	s_barrier
	s_branch .LBB0_628
